# P7 XN2 stores sc0 sc1 instead of sc1, on top of v102
# speedup vs baseline: 1.0177x; 1.0177x over previous
.LBB0_807:
	s_ashr_i32 s7, s6, 31
	s_lshl_b64 s[0:1], s[6:7], 6
	s_waitcnt lgkmcnt(0)
	v_lshl_add_u64 v[16:17], v[24:25], 0, s[0:1]
	global_load_dwordx4 v[30:33], v[16:17], off
	s_add_i32 s12, s3, s6
	s_cmp_lt_i32 s12, 0x8000
	s_cselect_b32 s0, s12, s6
	s_ashr_i32 s1, s0, 31
	s_lshl_b64 s[20:21], s[0:1], 6
	s_lshl_b64 s[14:15], s[0:1], 11
	s_lshl_b64 s[0:1], s[0:1], 2
	s_add_u32 s16, s30, s0
	s_addc_u32 s17, s31, s1
	s_lshl_b64 s[0:1], s[6:7], 11
	v_lshl_add_u64 v[28:29], v[22:23], 0, s[0:1]
	global_load_dwordx2 v[34:35], v[28:29], off offset:1536 nt
	v_lshl_add_u64 v[16:17], v[26:27], 0, s[0:1]
	s_lshl_b64 s[0:1], s[6:7], 2
	s_add_u32 s0, s30, s0
	s_addc_u32 s1, s31, s1
	global_load_dwordx2 v[36:37], v[16:17], off offset:512 nt
	global_load_dwordx2 v[38:39], v[28:29], off offset:512 nt
	global_load_dwordx2 v[40:41], v[16:17], off offset:1024 nt
	global_load_dwordx2 v[42:43], v[28:29], off offset:1024 nt
	global_load_dwordx2 v[44:45], v[16:17], off offset:1536 nt
	global_load_dwordx2 v[46:47], v[28:29], off nt
	global_load_dwordx2 v[56:57], v[16:17], off nt
	global_load_dword v58, v21, s[0:1]
	v_lshl_add_u64 v[16:17], v[24:25], 0, s[20:21]
	global_load_dwordx4 v[16:19], v[16:17], off
	s_cmpk_gt_i32 s12, 0x7fff
	s_waitcnt vmcnt(10)
	v_mov_b32_e32 v60, v31
	v_mov_b32_e32 v61, v32
	v_mov_b32_e32 v31, v33
	v_pk_add_f32 v[30:31], v[60:61], v[30:31]
	s_waitcnt vmcnt(8)
	v_and_b32_e32 v61, 0xffff0000, v36
	v_add_f32_e32 v30, v30, v31
	ds_bpermute_b32 v32, v20, v30
	v_and_b32_e32 v55, 0xffff0000, v35
	v_lshlrev_b32_e32 v59, 16, v35
	s_waitcnt vmcnt(4)
	v_lshlrev_b32_e32 v70, 16, v44
	v_and_b32_e32 v72, 0xffff0000, v44
	s_waitcnt lgkmcnt(0)
	v_add_f32_e32 v30, v30, v32
	ds_bpermute_b32 v32, v48, v30
	v_lshlrev_b32_e32 v74, 16, v45
	v_and_b32_e32 v76, 0xffff0000, v45
	s_waitcnt vmcnt(2)
	v_lshlrev_b32_e32 v44, 16, v57
	v_and_b32_e32 v45, 0xffff0000, v57
	s_waitcnt lgkmcnt(0)
	v_add_f32_e32 v30, v30, v32
	v_fmamk_f32 v30, v30, 0x3a800000, v53
	v_mul_f32_e32 v32, 0x4f800000, v30
	v_cmp_gt_f32_e32 vcc, s19, v30
	s_waitcnt vmcnt(1)
	v_mul_f32_e32 v57, v58, v55
	v_and_b32_e32 v31, 0xffff0000, v34
	v_cndmask_b32_e32 v30, v30, v32, vcc
	v_sqrt_f32_e32 v32, v30
	v_lshlrev_b32_e32 v33, 16, v34
	v_lshlrev_b32_e32 v35, 16, v36
	v_lshlrev_b32_e32 v34, 16, v38
	v_add_u32_e32 v55, -1, v32
	v_and_b32_e32 v60, 0xffff0000, v38
	v_lshlrev_b32_e32 v62, 16, v39
	v_and_b32_e32 v36, 0xffff0000, v39
	v_lshlrev_b32_e32 v39, 16, v40
	v_lshlrev_b32_e32 v38, 16, v42
	v_and_b32_e32 v65, 0xffff0000, v40
	v_and_b32_e32 v64, 0xffff0000, v42
	v_lshlrev_b32_e32 v66, 16, v43
	v_and_b32_e32 v40, 0xffff0000, v43
	v_lshlrev_b32_e32 v42, 16, v47
	v_and_b32_e32 v43, 0xffff0000, v47
	v_lshlrev_b32_e32 v68, 16, v46
	v_and_b32_e32 v69, 0xffff0000, v46
	v_lshlrev_b32_e32 v46, 16, v56
	v_and_b32_e32 v47, 0xffff0000, v56
	v_mul_f32_e32 v71, v58, v59
	v_add_u32_e32 v56, 1, v32
	v_fma_f32 v59, -v55, v32, v30
	v_fma_f32 v73, -v56, v32, v30
	v_cmp_ge_f32_e64 s[0:1], 0, v59
	v_lshlrev_b32_e32 v63, 16, v37
	v_and_b32_e32 v37, 0xffff0000, v37
	v_cndmask_b32_e64 v32, v32, v55, s[0:1]
	v_cmp_lt_f32_e64 s[0:1], 0, v73
	v_lshlrev_b32_e32 v67, 16, v41
	v_and_b32_e32 v41, 0xffff0000, v41
	v_cndmask_b32_e64 v32, v32, v56, s[0:1]
	v_mul_f32_e32 v55, 0x37800000, v32
	v_cndmask_b32_e32 v32, v32, v55, vcc
	v_cmp_class_f32_e32 vcc, v30, v54
	v_mov_b32_e32 v73, v58
	s_waitcnt vmcnt(0)
	v_add_f32_e32 v16, v16, v17
	v_cndmask_b32_e32 v30, v32, v30, vcc
	v_div_scale_f32 v32, s[0:1], v30, v30, 1.0
	v_rcp_f32_e32 v55, v32
	v_div_scale_f32 v56, vcc, 1.0, v30, 1.0
	v_add_f32_e32 v18, v18, v19
	v_fma_f32 v59, -v32, v55, 1.0
	v_fmac_f32_e32 v55, v59, v55
	v_mul_f32_e32 v59, v56, v55
	v_fma_f32 v75, -v32, v59, v56
	v_fmac_f32_e32 v59, v75, v55
	v_fma_f32 v32, -v32, v59, v56
	v_div_fmas_f32 v32, v32, v55, v59
	v_div_fixup_f32 v59, v32, v30, 1.0
	v_mov_b32_e32 v30, v59
	v_mul_f32_e32 v32, v59, v74
	v_pk_mul_f32 v[44:45], v[30:31], v[44:45] op_sel_hi:[0,1]
	v_pk_mul_f32 v[34:35], v[58:59], v[34:35]
	v_pk_mul_f32 v[60:61], v[58:59], v[60:61]
	v_pk_mul_f32 v[62:63], v[58:59], v[62:63]
	v_pk_mul_f32 v[36:37], v[58:59], v[36:37]
	v_pk_mul_f32 v[38:39], v[58:59], v[38:39]
	v_pk_mul_f32 v[64:65], v[58:59], v[64:65]
	v_pk_mul_f32 v[66:67], v[58:59], v[66:67]
	v_pk_mul_f32 v[40:41], v[58:59], v[40:41]
	v_mul_f32_e32 v75, v59, v70
	v_mul_f32_e32 v77, v59, v72
	v_mul_f32_e32 v55, v59, v76
	v_mul_f32_e32 v59, v2, v32
	v_pk_mul_f32 v[46:47], v[30:31], v[46:47] op_sel_hi:[0,1]
	v_pk_mul_f32 v[44:45], v[14:15], v[44:45]
	v_pk_mul_f32 v[46:47], v[12:13], v[46:47]
	v_pk_fma_f32 v[80:81], v[58:59], v[42:43], v[44:45] op_sel_hi:[0,1,1]
	v_pk_fma_f32 v[68:69], v[58:59], v[68:69], v[46:47] op_sel_hi:[0,1,1]
	v_pk_mov_b32 v[42:43], v[80:81], v[0:1] op_sel:[1,0]
	v_mov_b32_e32 v74, v81
	v_pk_mul_f32 v[42:43], v[42:43], v[74:75]
	v_pk_mov_b32 v[82:83], v[68:69], v[0:1] op_sel:[1,0]
	v_mov_b32_e32 v74, v69
	v_mov_b32_e32 v72, v80
	v_mov_b32_e32 v32, v80
	v_mov_b32_e32 v44, v68
	v_mov_b32_e32 v45, v58
	v_mov_b32_e32 v46, v68
	v_mov_b32_e32 v47, v33
	v_pk_mul_f32 v[74:75], v[82:83], v[74:75]
	v_pk_fma_f32 v[32:33], v[72:73], v[32:33], v[42:43]
	v_pk_fma_f32 v[72:73], v[44:45], v[46:47], v[74:75]
	v_mul_f32_e32 v79, v3, v55
	v_pk_add_f32 v[42:43], v[72:73], v[32:33]
	v_pk_mul_f32 v[32:33], v[72:73], v[32:33]
	v_add_f32_e32 v16, v16, v18
	v_mov_b32_e32 v43, v33
	v_mov_b32_e32 v32, v63
	v_mov_b32_e32 v33, v37
	v_mov_b32_e32 v63, v36
	v_mov_b32_e32 v36, v35
	v_mov_b32_e32 v37, v61
	v_mov_b32_e32 v35, v60
	v_pk_fma_f32 v[60:61], v[8:9], v[36:37], v[34:35]
	v_pk_fma_f32 v[62:63], v[10:11], v[32:33], v[62:63]
	v_mov_b32_e32 v36, v61
	v_mov_b32_e32 v37, v1
	v_mov_b32_e32 v76, v61
	v_mov_b32_e32 v32, v63
	v_mov_b32_e32 v33, v1
	v_mov_b32_e32 v34, v60
	v_mov_b32_e32 v35, v58
	v_mov_b32_e32 v30, v60
	v_pk_mul_f32 v[36:37], v[36:37], v[76:77]
	v_mov_b32_e32 v76, v63
	v_pk_fma_f32 v[74:75], v[34:35], v[30:31], v[36:37]
	v_mov_b32_e32 v34, v62
	v_mov_b32_e32 v30, v62
	v_pk_mul_f32 v[32:33], v[32:33], v[76:77]
	ds_bpermute_b32 v18, v20, v16
	v_pk_fma_f32 v[30:31], v[34:35], v[30:31], v[32:33]
	s_waitcnt lgkmcnt(0)
	v_add_f32_e32 v16, v16, v18
	v_pk_add_f32 v[32:33], v[74:75], v[30:31]
	v_pk_mul_f32 v[30:31], v[74:75], v[30:31]
	v_mov_b32_e32 v74, v73
	v_mov_b32_e32 v33, v31
	v_pk_add_f32 v[30:31], v[42:43], v[32:33]
	v_mov_b32_e32 v32, v67
	v_mov_b32_e32 v33, v41
	v_mov_b32_e32 v67, v40
	v_pk_fma_f32 v[66:67], v[6:7], v[32:33], v[66:67]
	s_nop 0
	v_mov_b32_e32 v78, v66
	v_mov_b32_e32 v56, v66
	v_pk_add_f32 v[56:57], v[78:79], v[56:57]
	v_mul_f32_e32 v32, v67, v67
	v_pk_fma_f32 v[32:33], v[66:67], v[66:67], v[32:33] op_sel_hi:[1,1,0]
	v_pk_mul_f32 v[34:35], v[56:57], v[56:57]
	s_nop 0
	v_mov_b32_e32 v33, v35
	v_mov_b32_e32 v34, v39
	v_mov_b32_e32 v35, v65
	v_mov_b32_e32 v39, v64
	v_pk_fma_f32 v[64:65], v[4:5], v[34:35], v[38:39]
	s_nop 0
	v_mov_b32_e32 v58, v64
	v_mov_b32_e32 v70, v64
	v_pk_add_f32 v[58:59], v[58:59], v[70:71]
	v_mul_f32_e32 v34, v65, v65
	v_pk_fma_f32 v[34:35], v[64:65], v[64:65], v[34:35] op_sel_hi:[1,1,0]
	v_pk_mul_f32 v[36:37], v[58:59], v[58:59]
	v_lshl_add_u64 v[70:71], v[26:27], 0, s[14:15]
	v_mov_b32_e32 v35, v37
	v_pk_add_f32 v[32:33], v[34:35], v[32:33]
	v_lshl_add_u64 v[34:35], v[22:23], 0, s[14:15]
	v_pk_add_f32 v[30:31], v[30:31], v[32:33]
	s_nop 0
	v_add_f32_e32 v31, v30, v31
	ds_bpermute_b32 v32, v20, v31
	global_load_dword v30, v21, s[16:17]
	s_waitcnt lgkmcnt(0)
	v_add_f32_e32 v31, v31, v32
	ds_bpermute_b32 v36, v48, v31
	global_load_dwordx2 v[32:33], v[34:35], off nt
	global_load_dwordx2 v[42:43], v[34:35], off offset:512 nt
	global_load_dwordx2 v[38:39], v[34:35], off offset:1024 nt
	global_load_dwordx2 v[46:47], v[34:35], off offset:1536 nt
	s_waitcnt lgkmcnt(0)
	v_add_f32_e32 v31, v31, v36
	global_load_dwordx2 v[34:35], v[70:71], off nt
	global_load_dwordx2 v[44:45], v[70:71], off offset:512 nt
	global_load_dwordx2 v[40:41], v[70:71], off offset:1024 nt
	global_load_dwordx2 v[36:37], v[70:71], off offset:1536 nt
	ds_bpermute_b32 v55, v49, v31
	s_waitcnt lgkmcnt(0)
	v_add_f32_e32 v31, v31, v55
	ds_bpermute_b32 v55, v50, v31
	s_waitcnt lgkmcnt(0)
	v_add_f32_e32 v31, v31, v55
	ds_bpermute_b32 v55, v51, v31
	s_waitcnt lgkmcnt(0)
	v_add_f32_e32 v31, v31, v55
	ds_bpermute_b32 v55, v52, v31
	s_waitcnt lgkmcnt(0)
	v_add_f32_e32 v17, v31, v55
	v_fmamk_f32 v17, v17, 0x3a800000, v53
	v_mul_f32_e32 v31, 0x4f800000, v17
	v_cmp_gt_f32_e32 vcc, s19, v17
	s_nop 1
	v_cndmask_b32_e32 v17, v17, v31, vcc
	v_sqrt_f32_e32 v31, v17
	s_nop 0
	v_add_u32_e32 v19, -1, v31
	v_fma_f32 v55, -v19, v31, v17
	v_cmp_ge_f32_e64 s[0:1], 0, v55
	v_add_u32_e32 v55, 1, v31
	s_nop 0
	v_cndmask_b32_e64 v19, v31, v19, s[0:1]
	v_fma_f32 v31, -v55, v31, v17
	v_cmp_lt_f32_e64 s[0:1], 0, v31
	s_nop 1
	v_cndmask_b32_e64 v19, v19, v55, s[0:1]
	v_mul_f32_e32 v31, 0x37800000, v19
	v_cndmask_b32_e32 v19, v19, v31, vcc
	v_cmp_class_f32_e32 vcc, v17, v54
	s_nop 1
	v_cndmask_b32_e32 v19, v19, v17, vcc
	v_div_scale_f32 v31, s[0:1], v19, v19, 1.0
	v_rcp_f32_e32 v55, v31
	ds_bpermute_b32 v17, v48, v16
	v_fma_f32 v18, -v31, v55, 1.0
	v_fmac_f32_e32 v55, v18, v55
	v_div_scale_f32 v18, vcc, 1.0, v19, 1.0
	v_mul_f32_e32 v56, v18, v55
	v_fma_f32 v58, -v31, v56, v18
	v_fmac_f32_e32 v56, v58, v55
	v_fma_f32 v18, -v31, v56, v18
	v_div_fmas_f32 v18, v18, v55, v56
	v_div_fixup_f32 v18, v18, v19, 1.0
	v_pk_mul_f32 v[60:61], v[18:19], v[60:61] op_sel_hi:[0,1]
	v_pk_mul_f32 v[62:63], v[18:19], v[62:63] op_sel_hi:[0,1]
	v_cvt_pk_bf16_f32 v60, v60, v61
	v_cvt_pk_bf16_f32 v61, v62, v63
	global_store_dwordx2 v[28:29], v[60:61], off offset:512 sc0 sc1
	v_pk_mul_f32 v[60:61], v[18:19], v[64:65] op_sel_hi:[0,1]
	v_pk_mul_f32 v[62:63], v[18:19], v[66:67] op_sel_hi:[0,1]
	v_cvt_pk_bf16_f32 v60, v60, v61
	v_cvt_pk_bf16_f32 v61, v62, v63
	v_mov_b32_e32 v56, v59
	v_pk_mul_f32 v[68:69], v[18:19], v[68:69] op_sel_hi:[0,1]
	v_pk_mul_f32 v[70:71], v[18:19], v[80:81] op_sel_hi:[0,1]
	global_store_dwordx2 v[28:29], v[60:61], off offset:1024 sc0 sc1
	v_pk_mul_f32 v[60:61], v[18:19], v[74:75] op_sel_hi:[0,1]
	v_pk_mul_f32 v[18:19], v[18:19], v[56:57] op_sel_hi:[0,1]
	v_cvt_pk_bf16_f32 v68, v68, v69
	v_cvt_pk_bf16_f32 v69, v70, v71
	v_cvt_pk_bf16_f32 v58, v60, v61
	v_cvt_pk_bf16_f32 v59, v18, v19
	global_store_dwordx2 v[28:29], v[68:69], off sc0 sc1
	global_store_dwordx2 v[28:29], v[58:59], off offset:1536 sc0 sc1
	s_cbranch_scc1 .LBB0_806
	s_waitcnt lgkmcnt(0)
	v_add_f32_e32 v16, v16, v17
	v_fmamk_f32 v16, v16, 0x3a800000, v53
	v_mul_f32_e32 v17, 0x4f800000, v16
	v_cmp_gt_f32_e32 vcc, s19, v16
	s_waitcnt vmcnt(8)
	v_lshlrev_b32_e32 v19, 16, v47
	s_waitcnt vmcnt(6)
	v_lshlrev_b32_e32 v57, 16, v44
	v_cndmask_b32_e32 v16, v16, v17, vcc
	v_sqrt_f32_e32 v18, v16
	v_and_b32_e32 v17, 0xffff0000, v47
	v_lshlrev_b32_e32 v47, 16, v46
	v_and_b32_e32 v59, 0xffff0000, v44
	v_add_u32_e32 v28, -1, v18
	v_fma_f32 v29, -v28, v18, v16
	v_cmp_ge_f32_e64 s[0:1], 0, v29
	v_add_u32_e32 v29, 1, v18
	v_lshlrev_b32_e32 v61, 16, v45
	v_cndmask_b32_e64 v28, v18, v28, s[0:1]
	v_fma_f32 v18, -v29, v18, v16
	v_cmp_lt_f32_e64 s[0:1], 0, v18
	v_and_b32_e32 v45, 0xffff0000, v45
	v_and_b32_e32 v44, 0xffff0000, v43
	v_cndmask_b32_e64 v18, v28, v29, s[0:1]
	v_mul_f32_e32 v28, 0x37800000, v18
	v_cndmask_b32_e32 v18, v18, v28, vcc
	v_cmp_class_f32_e32 vcc, v16, v54
	v_and_b32_e32 v29, 0xffff0000, v46
	v_lshlrev_b32_e32 v56, 16, v42
	v_cndmask_b32_e32 v16, v18, v16, vcc
	v_div_scale_f32 v18, s[0:1], v16, v16, 1.0
	v_rcp_f32_e32 v28, v18
	v_and_b32_e32 v58, 0xffff0000, v42
	v_lshlrev_b32_e32 v60, 16, v43
	s_waitcnt vmcnt(5)
	v_and_b32_e32 v63, 0xffff0000, v40
	v_fma_f32 v31, -v18, v28, 1.0
	v_fmac_f32_e32 v28, v31, v28
	v_div_scale_f32 v31, vcc, 1.0, v16, 1.0
	v_mul_f32_e32 v46, v31, v28
	v_fma_f32 v55, -v18, v46, v31
	v_fmac_f32_e32 v46, v55, v28
	v_fma_f32 v18, -v18, v46, v31
	v_div_fmas_f32 v18, v18, v28, v46
	v_div_fixup_f32 v31, v18, v16, 1.0
	v_pk_mul_f32 v[42:43], v[30:31], v[44:45]
	v_lshlrev_b32_e32 v45, 16, v40
	v_lshlrev_b32_e32 v65, 16, v41
	v_and_b32_e32 v41, 0xffff0000, v41
	v_and_b32_e32 v40, 0xffff0000, v39
	s_waitcnt vmcnt(4)
	v_lshlrev_b32_e32 v16, 16, v36
	v_lshlrev_b32_e32 v44, 16, v38
	v_and_b32_e32 v62, 0xffff0000, v38
	v_lshlrev_b32_e32 v64, 16, v39
	v_pk_mul_f32 v[38:39], v[30:31], v[40:41]
	v_mul_f32_e32 v41, v31, v16
	v_and_b32_e32 v16, 0xffff0000, v36
	v_mul_f32_e32 v67, v31, v16
	v_lshlrev_b32_e32 v16, 16, v37
	v_mul_f32_e32 v16, v31, v16
	v_mul_f32_e32 v69, v2, v16
	v_and_b32_e32 v16, 0xffff0000, v37
	v_mul_f32_e32 v16, v31, v16
	v_mul_f32_e32 v17, v30, v17
	v_mul_f32_e32 v37, v3, v16
	v_lshlrev_b32_e32 v72, 16, v35
	v_and_b32_e32 v73, 0xffff0000, v35
	v_mov_b32_e32 v16, v31
	v_pk_mul_f32 v[72:73], v[16:17], v[72:73] op_sel_hi:[0,1]
	v_lshlrev_b32_e32 v70, 16, v33
	v_and_b32_e32 v71, 0xffff0000, v33
	v_pk_mul_f32 v[72:73], v[14:15], v[72:73]
	v_and_b32_e32 v33, 0xffff0000, v34
	v_pk_fma_f32 v[70:71], v[30:31], v[70:71], v[72:73] op_sel_hi:[0,1,1]
	v_lshlrev_b32_e32 v72, 16, v32
	v_and_b32_e32 v73, 0xffff0000, v32
	v_lshlrev_b32_e32 v32, 16, v34
	v_pk_mul_f32 v[32:33], v[16:17], v[32:33] op_sel_hi:[0,1]
	v_pk_mul_f32 v[32:33], v[12:13], v[32:33]
	v_mov_b32_e32 v40, v71
	v_pk_fma_f32 v[32:33], v[30:31], v[72:73], v[32:33] op_sel_hi:[0,1,1]
	v_pk_mov_b32 v[72:73], v[70:71], v[0:1] op_sel:[1,0]
	v_pk_mov_b32 v[78:79], v[32:33], v[0:1] op_sel:[1,0]
	v_pk_mul_f32 v[72:73], v[72:73], v[40:41]
	v_mov_b32_e32 v40, v33
	v_mov_b32_e32 v34, v70
	v_mov_b32_e32 v35, v30
	v_mov_b32_e32 v46, v70
	v_mov_b32_e32 v74, v32
	v_mov_b32_e32 v75, v30
	v_mov_b32_e32 v76, v32
	v_mov_b32_e32 v77, v47
	v_pk_mul_f32 v[40:41], v[78:79], v[40:41]
	v_pk_fma_f32 v[34:35], v[34:35], v[46:47], v[72:73]
	v_pk_fma_f32 v[40:41], v[74:75], v[76:77], v[40:41]
	v_pk_mul_f32 v[60:61], v[30:31], v[60:61]
	v_pk_add_f32 v[46:47], v[40:41], v[34:35]
	v_pk_mul_f32 v[34:35], v[40:41], v[34:35]
	v_pk_mul_f32 v[56:57], v[30:31], v[56:57]
	v_pk_mul_f32 v[58:59], v[30:31], v[58:59]
	v_mov_b32_e32 v47, v35
	v_mov_b32_e32 v34, v61
	v_mov_b32_e32 v35, v43
	v_mov_b32_e32 v61, v42
	v_pk_fma_f32 v[34:35], v[10:11], v[34:35], v[60:61]
	v_mov_b32_e32 v60, v57
	v_mov_b32_e32 v61, v59
	v_mov_b32_e32 v57, v58
	v_pk_fma_f32 v[56:57], v[8:9], v[60:61], v[56:57]
	v_mov_b32_e32 v61, v1
	v_mov_b32_e32 v60, v57
	v_mov_b32_e32 v66, v57
	v_mov_b32_e32 v42, v35
	v_mov_b32_e32 v43, v1
	v_mov_b32_e32 v58, v56
	v_mov_b32_e32 v59, v30
	v_mov_b32_e32 v28, v56
	v_pk_mul_f32 v[60:61], v[60:61], v[66:67]
	v_mov_b32_e32 v66, v35
	v_mul_f32_e32 v19, v30, v19
	v_pk_mul_f32 v[44:45], v[30:31], v[44:45]
	v_pk_mul_f32 v[62:63], v[30:31], v[62:63]
	v_pk_mul_f32 v[64:65], v[30:31], v[64:65]
	v_pk_fma_f32 v[58:59], v[58:59], v[28:29], v[60:61]
	v_mov_b32_e32 v60, v34
	v_mov_b32_e32 v61, v30
	v_mov_b32_e32 v28, v34
	v_pk_mul_f32 v[30:31], v[42:43], v[66:67]
	s_ashr_i32 s13, s12, 31
	v_pk_fma_f32 v[28:29], v[60:61], v[28:29], v[30:31]
	s_nop 0
	v_pk_add_f32 v[30:31], v[58:59], v[28:29]
	v_pk_mul_f32 v[28:29], v[58:59], v[28:29]
	v_mov_b32_e32 v58, v41
	v_mov_b32_e32 v31, v29
	v_pk_add_f32 v[28:29], v[46:47], v[30:31]
	v_mov_b32_e32 v30, v65
	v_mov_b32_e32 v31, v39
	v_mov_b32_e32 v65, v38
	v_pk_fma_f32 v[30:31], v[6:7], v[30:31], v[64:65]
	s_nop 0
	v_mov_b32_e32 v36, v30
	v_mov_b32_e32 v16, v30
	v_pk_add_f32 v[16:17], v[36:37], v[16:17]
	v_mul_f32_e32 v18, v31, v31
	v_pk_fma_f32 v[36:37], v[30:31], v[30:31], v[18:19] op_sel_hi:[1,1,0]
	v_pk_mul_f32 v[38:39], v[16:17], v[16:17]
	s_nop 0
	v_mov_b32_e32 v37, v39
	v_mov_b32_e32 v38, v45
	v_mov_b32_e32 v39, v63
	v_mov_b32_e32 v45, v62
	v_pk_fma_f32 v[38:39], v[4:5], v[38:39], v[44:45]
	s_nop 0
	v_mov_b32_e32 v68, v38
	v_mov_b32_e32 v18, v38
	v_pk_add_f32 v[18:19], v[68:69], v[18:19]
	v_mul_f32_e32 v16, v39, v39
	v_pk_fma_f32 v[42:43], v[38:39], v[38:39], v[16:17] op_sel_hi:[1,1,0]
	v_pk_mul_f32 v[44:45], v[18:19], v[18:19]
	s_nop 0
	v_mov_b32_e32 v43, v45
	v_pk_add_f32 v[36:37], v[42:43], v[36:37]
	s_nop 0
	v_pk_add_f32 v[28:29], v[28:29], v[36:37]
	s_nop 0
	v_add_f32_e32 v16, v28, v29
	ds_bpermute_b32 v18, v20, v16
	s_waitcnt lgkmcnt(0)
	v_add_f32_e32 v16, v16, v18
	ds_bpermute_b32 v18, v48, v16
	s_waitcnt lgkmcnt(0)
	v_add_f32_e32 v16, v16, v18
	ds_bpermute_b32 v18, v49, v16
	s_waitcnt lgkmcnt(0)
	v_add_f32_e32 v16, v16, v18
	ds_bpermute_b32 v18, v50, v16
	s_waitcnt lgkmcnt(0)
	v_add_f32_e32 v16, v16, v18
	ds_bpermute_b32 v18, v51, v16
	s_waitcnt lgkmcnt(0)
	v_add_f32_e32 v16, v16, v18
	ds_bpermute_b32 v18, v52, v16
	s_waitcnt lgkmcnt(0)
	v_add_f32_e32 v16, v16, v18
	v_fmamk_f32 v16, v16, 0x3a800000, v53
	v_mul_f32_e32 v18, 0x4f800000, v16
	v_cmp_gt_f32_e32 vcc, s19, v16
	s_nop 1
	v_cndmask_b32_e32 v16, v16, v18, vcc
	v_sqrt_f32_e32 v18, v16
	s_nop 0
	v_add_u32_e32 v28, -1, v18
	v_fma_f32 v29, -v28, v18, v16
	v_cmp_ge_f32_e64 s[0:1], 0, v29
	v_add_u32_e32 v29, 1, v18
	s_nop 0
	v_cndmask_b32_e64 v28, v18, v28, s[0:1]
	v_fma_f32 v18, -v29, v18, v16
	v_cmp_lt_f32_e64 s[0:1], 0, v18
	s_nop 1
	v_cndmask_b32_e64 v18, v28, v29, s[0:1]
	v_mul_f32_e32 v28, 0x37800000, v18
	v_cndmask_b32_e32 v18, v18, v28, vcc
	v_cmp_class_f32_e32 vcc, v16, v54
	s_nop 1
	v_cndmask_b32_e32 v16, v18, v16, vcc
	v_div_scale_f32 v18, s[0:1], v16, v16, 1.0
	v_rcp_f32_e32 v36, v18
	s_lshl_b64 s[0:1], s[12:13], 11
	v_lshl_add_u64 v[28:29], v[22:23], 0, s[0:1]
	v_fma_f32 v37, -v18, v36, 1.0
	v_fmac_f32_e32 v36, v37, v36
	v_div_scale_f32 v37, vcc, 1.0, v16, 1.0
	v_mul_f32_e32 v40, v37, v36
	v_fma_f32 v42, -v18, v40, v37
	v_fmac_f32_e32 v40, v42, v36
	v_fma_f32 v18, -v18, v40, v37
	v_div_fmas_f32 v18, v18, v36, v40
	v_div_fixup_f32 v18, v18, v16, 1.0
	v_pk_mul_f32 v[32:33], v[18:19], v[32:33] op_sel_hi:[0,1]
	v_pk_mul_f32 v[36:37], v[18:19], v[70:71] op_sel_hi:[0,1]
	v_cvt_pk_bf16_f32 v32, v32, v33
	v_cvt_pk_bf16_f32 v33, v36, v37
	global_store_dwordx2 v[28:29], v[32:33], off sc0 sc1
	v_pk_mul_f32 v[32:33], v[18:19], v[56:57] op_sel_hi:[0,1]
	v_pk_mul_f32 v[34:35], v[18:19], v[34:35] op_sel_hi:[0,1]
	v_cvt_pk_bf16_f32 v32, v32, v33
	v_cvt_pk_bf16_f32 v33, v34, v35
	global_store_dwordx2 v[28:29], v[32:33], off offset:512 sc0 sc1
	v_pk_mul_f32 v[32:33], v[18:19], v[38:39] op_sel_hi:[0,1]
	v_pk_mul_f32 v[30:31], v[18:19], v[30:31] op_sel_hi:[0,1]
	v_mov_b32_e32 v16, v19
	v_cvt_pk_bf16_f32 v32, v32, v33
	v_cvt_pk_bf16_f32 v33, v30, v31
	v_pk_mul_f32 v[30:31], v[18:19], v[58:59] op_sel_hi:[0,1]
	v_pk_mul_f32 v[16:17], v[18:19], v[16:17] op_sel_hi:[0,1]
	v_cvt_pk_bf16_f32 v30, v30, v31
	v_cvt_pk_bf16_f32 v31, v16, v17
	global_store_dwordx2 v[28:29], v[32:33], off offset:1024 sc0 sc1
	global_store_dwordx2 v[28:29], v[30:31], off offset:1536 sc0 sc1
	s_branch .LBB0_806
